# attention K/V tile DMAs issued with SGPR bases and scalar slot arithmetic (no per-tile 64-bit VALU adds or readfirstlanes)
# baseline (speedup 1.0000x reference)
.LBB0_561:
	v_mov_b32_e32 v5, v0
	v_mov_b32_e32 v3, v115
	v_readfirstlane_b32 s11, v5
	s_ashr_i32 s33, s11, 6
	s_lshl_b32 s9, s33, 5
	s_add_i32 s0, s9, s10
	s_ashr_i32 s1, s0, 31
	s_lshl_b64 s[74:75], s[0:1], 11
	s_lshl_b64 s[4:5], s[0:1], 12
	s_add_u32 s1, s68, s4
	s_addc_u32 s4, s69, s5
	s_lshl_b32 s91, s6, 7
	s_lshl_b32 s5, s6, 8
	s_add_u32 s1, s1, s5
	s_addc_u32 s5, s4, 0
	s_lshl_b32 s4, s86, 7
	v_and_b32_e32 v130, 31, v5
	s_add_u32 s4, s1, s4
	v_bfe_u32 v8, v5, 5, 1
	s_addc_u32 s5, s5, 0
	v_lshlrev_b32_e32 v2, 12, v130
	v_lshl_add_u64 v[6:7], s[4:5], 0, v[2:3]
	v_lshlrev_b32_e32 v2, 4, v8
	v_lshl_add_u64 v[6:7], v[6:7], 0, v[2:3]
	global_load_dwordx4 v[98:101], v[6:7], off
	global_load_dwordx4 v[102:105], v[6:7], off offset:32
	global_load_dwordx4 v[106:109], v[6:7], off offset:64
	global_load_dwordx4 v[110:113], v[6:7], off offset:96
	v_mul_f32_e32 v3, 0x4f800000, v4
	v_cmp_gt_f32_e32 vcc, s18, v4
	v_lshlrev_b32_e32 v10, 2, v8
	v_lshlrev_b32_e32 v131, 10, v8
	v_cndmask_b32_e32 v3, v4, v3, vcc
	v_sqrt_f32_e32 v4, v3
	v_lshlrev_b32_e32 v8, 4, v130
	v_add3_u32 v132, 0, v131, v8
	s_waitcnt vmcnt(0)
	v_add_u32_e32 v8, -1, v4
	v_add_u32_e32 v11, 1, v4
	v_fma_f32 v12, -v8, v4, v3
	v_fma_f32 v13, -v11, v4, v3
	v_cmp_ge_f32_e64 s[4:5], 0, v12
	s_mov_b32 s7, s85
	s_or_b32 s84, s84, s86
	v_cndmask_b32_e64 v4, v4, v8, s[4:5]
	v_cmp_lt_f32_e64 s[4:5], 0, v13
	s_lshl_b32 s12, s33, 9
	s_and_b32 s14, s11, 0x3fffffc0
	v_cndmask_b32_e64 v4, v4, v11, s[4:5]
	v_mul_f32_e32 v8, 0x37800000, v4
	v_cndmask_b32_e32 v4, v4, v8, vcc
	v_cmp_class_f32_e32 vcc, v3, v124
	s_lshl_b64 s[6:7], s[6:7], 22
	s_lshl_b64 s[4:5], s[84:85], 21
	v_cndmask_b32_e32 v3, v4, v3, vcc
	s_ashr_i32 s13, s12, 31
	v_readlane_b32 s16, v244, 9
	v_readlane_b32 s17, v244, 10
	s_add_u32 s1, s16, s6
	s_addc_u32 s11, s17, s7
	s_lshl_b64 s[6:7], s[12:13], 1
	s_add_u32 s12, s1, s6
	s_addc_u32 s13, s11, s7
	s_lshl_b32 s15, s33, 10
	s_addk_i32 s10, 0x100
	s_add_i32 s76, s15, s90
	s_lshr_b32 s1, s10, 6
	v_and_b32_e32 v6, 63, v5
	v_bfe_u32 v116, v5, 4, 2
	v_lshlrev_b32_e32 v7, 1, v5
	v_lshlrev_b32_e32 v9, 3, v5
	v_and_b32_e32 v129, 15, v5
	v_bfe_u32 v5, v5, 2, 2
	s_add_u32 s4, s62, s4
	v_or_b32_e32 v5, v10, v5
	s_addc_u32 s5, s63, s5
	s_add_u32 s4, s4, s6
	v_lshlrev_b32_e32 v114, 4, v6
	s_addc_u32 s5, s5, s7
	v_lshl_add_u64 v[122:123], s[4:5], 0, v[114:115]
	s_mov_b64 s[98:99], s[4:5]
	v_mov_b32_e32 v189, v114
	s_add_i32 s84, s1, -4
	s_add_i32 s77, s15, 0
	s_lshl_b32 s6, s14, 2
	v_lshl_add_u64 v[118:119], s[12:13], 0, v[114:115]
	s_mov_b64 s[100:101], s[12:13]
	s_mov_b64 s[10:11], 0x2000
	s_add_i32 s6, s6, 0
	v_lshl_add_u64 v[120:121], v[118:119], 0, s[10:11]
	s_add_i32 s10, s6, 0x12000
	s_add_i32 s88, s77, 0x8000
	v_and_b32_e32 v9, 24, v9
	v_add_u32_e32 v114, s10, v2
	s_mov_b64 s[94:95], s[68:69]
	s_sub_i32 s89, s1, s8
	s_mov_b64 s[96:97], s[62:63]
	s_waitcnt vmcnt(3)
	s_nop 0
	v_and_b32_e32 v8, 0xffff0000, v98
	v_lshlrev_b32_e32 v4, 16, v98
	v_mul_f32_e32 v8, v8, v8
	v_lshlrev_b32_e32 v11, 16, v99
	v_fmac_f32_e32 v8, v4, v4
	v_and_b32_e32 v12, 0xffff0000, v99
	v_fmac_f32_e32 v8, v11, v11
	v_lshlrev_b32_e32 v13, 16, v100
	v_fmac_f32_e32 v8, v12, v12
	v_and_b32_e32 v14, 0xffff0000, v100
	v_fmac_f32_e32 v8, v13, v13
	v_lshlrev_b32_e32 v15, 16, v101
	v_fmac_f32_e32 v8, v14, v14
	v_and_b32_e32 v16, 0xffff0000, v101
	v_fmac_f32_e32 v8, v15, v15
	s_waitcnt vmcnt(2)
	v_fmac_f32_e32 v8, v16, v16
	v_lshlrev_b32_e32 v4, 16, v102
	v_fmac_f32_e32 v8, v4, v4
	v_and_b32_e32 v4, 0xffff0000, v102
	v_fmac_f32_e32 v8, v4, v4
	v_lshlrev_b32_e32 v4, 16, v103
	v_fmac_f32_e32 v8, v4, v4
	v_and_b32_e32 v4, 0xffff0000, v103
	v_fmac_f32_e32 v8, v4, v4
	v_lshlrev_b32_e32 v4, 16, v104
	v_fmac_f32_e32 v8, v4, v4
	v_and_b32_e32 v4, 0xffff0000, v104
	v_fmac_f32_e32 v8, v4, v4
	v_lshlrev_b32_e32 v4, 16, v105
	v_fmac_f32_e32 v8, v4, v4
	v_and_b32_e32 v4, 0xffff0000, v105
	s_waitcnt vmcnt(1)
	v_fmac_f32_e32 v8, v4, v4
	v_lshlrev_b32_e32 v4, 16, v106
	v_fmac_f32_e32 v8, v4, v4
	v_and_b32_e32 v4, 0xffff0000, v106
	v_fmac_f32_e32 v8, v4, v4
	v_lshlrev_b32_e32 v4, 16, v107
	v_fmac_f32_e32 v8, v4, v4
	v_and_b32_e32 v4, 0xffff0000, v107
	v_fmac_f32_e32 v8, v4, v4
	v_lshlrev_b32_e32 v4, 16, v108
	v_fmac_f32_e32 v8, v4, v4
	v_and_b32_e32 v4, 0xffff0000, v108
	v_fmac_f32_e32 v8, v4, v4
	v_lshlrev_b32_e32 v4, 16, v109
	v_fmac_f32_e32 v8, v4, v4
	v_and_b32_e32 v4, 0xffff0000, v109
	s_waitcnt vmcnt(0)
	v_fmac_f32_e32 v8, v4, v4
	v_lshlrev_b32_e32 v4, 16, v110
	v_fmac_f32_e32 v8, v4, v4
	v_and_b32_e32 v4, 0xffff0000, v110
	v_fmac_f32_e32 v8, v4, v4
	v_lshlrev_b32_e32 v4, 16, v111
	v_fmac_f32_e32 v8, v4, v4
	v_and_b32_e32 v4, 0xffff0000, v111
	v_fmac_f32_e32 v8, v4, v4
	v_lshlrev_b32_e32 v4, 16, v112
	v_fmac_f32_e32 v8, v4, v4
	v_and_b32_e32 v4, 0xffff0000, v112
	v_fmac_f32_e32 v8, v4, v4
	v_lshlrev_b32_e32 v4, 16, v113
	v_fmac_f32_e32 v8, v4, v4
	v_and_b32_e32 v4, 0xffff0000, v113
	v_fmac_f32_e32 v8, v4, v4
	v_mov_b32_e32 v4, v8
	s_nop 1
	v_permlane32_swap_b32_e32 v8, v4
	v_add_f32_e32 v4, v8, v4
	v_mul_f32_e32 v8, 0x4f800000, v4
	v_cmp_gt_f32_e32 vcc, s18, v4
	v_lshlrev_b32_e32 v11, 6, v5
	v_and_or_b32 v2, v7, 32, v11
	v_cndmask_b32_e32 v4, v4, v8, vcc
	v_sqrt_f32_e32 v8, v4
	v_add3_u32 v152, v9, s90, v2
	v_or_b32_e32 v2, s9, v130
	v_sub_u32_e32 v153, 0xbf, v2
	v_add_u32_e32 v5, -1, v8
	v_fma_f32 v12, -v5, v8, v4
	v_cmp_ge_f32_e64 s[4:5], 0, v12
	v_add_u32_e32 v12, 1, v8
	v_mov_b32_e32 v2, 0
	v_cndmask_b32_e64 v5, v8, v5, s[4:5]
	v_fma_f32 v8, -v12, v8, v4
	v_cmp_lt_f32_e64 s[4:5], 0, v8
	v_mov_b32_e32 v16, v2
	v_mov_b32_e32 v17, v2
	v_cndmask_b32_e64 v5, v5, v12, s[4:5]
	v_mul_f32_e32 v8, 0x37800000, v5
	v_cndmask_b32_e32 v5, v5, v8, vcc
	v_cmp_class_f32_e32 vcc, v4, v124
	s_lshl_b64 s[4:5], s[84:85], 13
	v_mov_b32_e32 v7, v2
	v_cndmask_b32_e32 v4, v5, v4, vcc
	v_mul_f32_e32 v3, v3, v4
	v_lshl_add_u64 v[4:5], v[122:123], 0, s[4:5]
	s_mov_b32 s4, m0
	s_mov_b32 m0, s77
	s_nop 0
	global_load_lds_dwordx4 v[4:5], off
	s_mov_b32 m0, s4
	s_lshl_b64 s[4:5], s[84:85], 14
	v_lshl_add_u64 v[4:5], v[118:119], 0, s[4:5]
	s_mov_b32 s6, m0
	s_mov_b32 m0, s76
	s_nop 0
	global_load_lds_dwordx4 v[4:5], off
	s_mov_b32 m0, s6
	v_lshl_add_u64 v[4:5], v[120:121], 0, s[4:5]
	s_mov_b32 s4, m0
	s_mov_b32 m0, s88
	s_nop 0
	global_load_lds_dwordx4 v[4:5], off
	s_mov_b32 m0, s4
	s_add_i32 s4, s1, -3
	s_mov_b32 s5, s85
	s_lshl_b64 s[6:7], s[4:5], 13
	v_lshl_add_u64 v[4:5], v[122:123], 0, s[6:7]
	s_add_i32 s6, s77, 0x2000
	s_mov_b32 s7, m0
	s_mov_b32 m0, s6
	s_nop 0
	global_load_lds_dwordx4 v[4:5], off
	s_mov_b32 m0, s7
	s_lshl_b64 s[4:5], s[4:5], 14
	v_lshl_add_u64 v[4:5], v[118:119], 0, s[4:5]
	s_add_i32 s6, s77, 0xa000
	s_mov_b32 s7, m0
	s_mov_b32 m0, s6
	s_nop 0
	global_load_lds_dwordx4 v[4:5], off
	s_mov_b32 m0, s7
	v_lshl_add_u64 v[4:5], v[120:121], 0, s[4:5]
	s_add_i32 s4, s77, 0xc000
	s_mov_b32 s5, m0
	s_mov_b32 m0, s4
	s_nop 0
	global_load_lds_dwordx4 v[4:5], off
	s_mov_b32 m0, s5
	v_fmamk_f32 v150, v3, 0x3f8020c5, v125
	v_or_b32_e32 v3, s0, v130
	s_lshl_b32 s0, s33, 2
	s_add_i32 s68, s0, 0
	v_sub_u32_e32 v151, v10, v3
	v_cmp_gt_u32_e64 s[4:5], 32, v6
	v_cmp_eq_u32_e64 s[6:7], 0, v6
	v_mov_b32_e32 v3, v2
	v_mov_b32_e32 v4, v2
	v_mov_b32_e32 v5, v2
	v_mov_b32_e32 v6, v2
	v_mov_b32_e32 v8, v2
	v_mov_b32_e32 v9, v2
	v_mov_b32_e32 v10, v2
	v_mov_b32_e32 v11, v2
	v_mov_b32_e32 v12, v2
	v_mov_b32_e32 v13, v2
	v_mov_b32_e32 v14, v2
	v_mov_b32_e32 v15, v2
	v_mov_b64_e32 v[64:65], v[16:17]
	v_mov_b64_e32 v[48:49], v[16:17]
	v_mov_b64_e32 v[32:33], v[16:17]
	v_mul_f32_e32 v133, 0, v117
	v_add_f32_e32 v134, v117, v117
	v_mul_f32_e32 v135, 0x40400000, v117
	v_mul_f32_e32 v136, 0x41000000, v117
	v_mul_f32_e32 v137, 0x41100000, v117
	v_mul_f32_e32 v138, 0x41200000, v117
	v_mul_f32_e32 v139, 0x41300000, v117
	v_mul_f32_e32 v140, 0x41800000, v117
	v_mul_f32_e32 v141, 0x41880000, v117
	v_mul_f32_e32 v142, 0x41900000, v117
	v_mul_f32_e32 v143, 0x41980000, v117
	v_mul_f32_e32 v144, 0x41c00000, v117
	v_mul_f32_e32 v145, 0x41c80000, v117
	v_mul_f32_e32 v146, 0x41d00000, v117
	v_mul_f32_e32 v148, 0x41d80000, v117
	v_mul_f32_e32 v149, 0x42000000, v117
	s_add_i32 s68, s68, 0x22800
	v_lshl_add_u32 v147, v130, 2, s10
	s_max_i32 s69, s89, 0
	s_mov_b32 s80, 0
	v_mov_b64_e32 v[62:63], v[14:15]
	v_mov_b64_e32 v[60:61], v[12:13]
	v_mov_b64_e32 v[58:59], v[10:11]
	v_mov_b64_e32 v[56:57], v[8:9]
	v_mov_b64_e32 v[54:55], v[6:7]
	v_mov_b64_e32 v[52:53], v[4:5]
	v_mov_b64_e32 v[50:51], v[2:3]
	v_mov_b64_e32 v[46:47], v[14:15]
	v_mov_b64_e32 v[44:45], v[12:13]
	v_mov_b64_e32 v[42:43], v[10:11]
	v_mov_b64_e32 v[40:41], v[8:9]
	v_mov_b64_e32 v[38:39], v[6:7]
	v_mov_b64_e32 v[36:37], v[4:5]
	v_mov_b64_e32 v[34:35], v[2:3]
	v_mov_b64_e32 v[30:31], v[14:15]
	v_mov_b64_e32 v[28:29], v[12:13]
	v_mov_b64_e32 v[26:27], v[10:11]
	v_mov_b64_e32 v[24:25], v[8:9]
	v_mov_b64_e32 v[22:23], v[6:7]
	v_mov_b64_e32 v[20:21], v[4:5]
	v_mov_b64_e32 v[18:19], v[2:3]
	s_mov_b32 s83, 0
	s_mov_b32 s81, 0
	v_mov_b32_e32 v154, v2
	v_mov_b32_e32 v155, v2
	s_cmp_eq_u32 s69, s83
	s_cbranch_scc0 .LBB0_563

.LBB0_570:
	s_add_i32 s8, s84, s83
	s_add_i32 s9, s84, s87
	s_add_i32 s10, s83, 2
	s_cmp_ge_i32 s10, s89
	s_cbranch_scc1 .LBB0_572
	s_sub_i32 s32, s81, 1
	s_cmp_eq_u32 s81, 0
	s_cselect_b32 s32, 2, s32
	s_add_i32 s10, s8, 2
	s_add_i32 s11, s9, 1
	s_cmp_lt_u32 s83, 2
	s_cselect_b32 s10, s10, s11
	s_ashr_i32 s11, s10, 31
	s_lshl_b64 s[12:13], s[10:11], 13
	s_add_u32 s12, s98, s12
	s_addc_u32 s13, s99, s13
	s_lshl_b64 s[10:11], s[10:11], 14
	s_add_u32 s10, s100, s10
	s_addc_u32 s11, s101, s11
	s_lshl_b32 s32, s32, 13
	s_add_i32 m0, s77, s32
	s_nop 0
	global_load_lds_dwordx4 v189, s[12:13]
	s_lshl_b32 s32, s32, 1
	s_add_i32 m0, s76, s32
	s_nop 0
	global_load_lds_dwordx4 v189, s[10:11]
	s_add_u32 s10, s10, 0x2000
	s_addc_u32 s11, s11, 0
	s_add_i32 m0, s88, s32
	s_nop 0
	global_load_lds_dwordx4 v189, s[10:11]
